# GEMM loops: stepped vmcnt waits interleaved with the 8 LDS staging writes instead of one wait in front
# speedup vs baseline: 1.0075x; 1.0003x over previous
; #define G_LOAD(RA, RB, KT) { _Pragma("unroll") for (int i = 0; i < 4; i++) { \
;       RA[i] = *(const u32x4*)(Ap + (size_t)(i * 32) * lda + (KT) * 64); RB[i] = *(const u32x4*)(Bp + (size_t)(i * 32) * ldb + (KT) * 64); } }
; #define G_STORE(RA, RB) { _Pragma("unroll") for (int i = 0; i < 4; i++) { \
;       *(u32x4*)(As + (lrow + i * 32) * GLD + lcc * 8) = RA[i]; *(u32x4*)(Bs + (lrow + i * 32) * GLD + lcc * 8) = RB[i]; } }
; template <class Epi>
; DEV void gemm_tile(const bf16_t* __restrict__ A, int lda, const bf16_t* __restrict__ Bt, int ldb, int K, int m0, int n0,
;                    Epi& epi, char* smem) {
;     ...
;   G_LOAD(ra0, rb0, 0);
;   G_LOAD(ra1, rb1, 1);
;   for (int kt = 0; kt < nk; kt += 2) {
;     __syncthreads();
;     G_STORE(ra0, rb0);
;     __syncthreads();
;     if (kt + 2 < nk) G_LOAD(ra0, rb0, kt + 2);
.LBB0_182:
	s_add_i32 s12, s12, 2
	s_cmp_gt_u32 s12, 13
	s_cselect_b64 s[14:15], -1, 0
	s_and_b64 vcc, exec, s[14:15]
	v_lshl_add_u64 v[142:143], v[138:139], 0, v[0:1]
	v_lshl_add_u64 v[140:141], v[136:137], 0, v[0:1]
	s_waitcnt lgkmcnt(0)
	s_barrier
	s_waitcnt vmcnt(15)
	ds_write_b128 v134, v[2:5]
	s_waitcnt vmcnt(14)
	ds_write_b128 v134, v[10:13] offset:20480
	s_waitcnt vmcnt(13)
	ds_write_b128 v134, v[18:21] offset:5120
	s_waitcnt vmcnt(12)
	ds_write_b128 v134, v[26:29] offset:25600
	s_waitcnt vmcnt(11)
	ds_write_b128 v134, v[34:37] offset:10240
	s_waitcnt vmcnt(10)
	ds_write_b128 v134, v[42:45] offset:30720
	s_waitcnt vmcnt(9)
	ds_write_b128 v134, v[50:53] offset:15360
	s_waitcnt vmcnt(8)
	ds_write_b128 v134, v[58:61] offset:35840
	s_waitcnt lgkmcnt(0)
	s_barrier
	s_cbranch_vccnz .Lgw_skip_0
	v_add_co_u32_e32 v2, vcc, 0x4200000, v142
	s_nop 1
	v_addc_co_u32_e32 v3, vcc, 0, v143, vcc
	v_add_co_u32_e32 v10, vcc, 0xba00000, v140
	global_load_dwordx4 v[2:5], v[2:3], off offset:256
	s_nop 0
	v_addc_co_u32_e32 v11, vcc, 0, v141, vcc
	v_add_co_u32_e32 v18, vcc, 0x4211000, v142
	global_load_dwordx4 v[10:13], v[10:11], off offset:256
	s_nop 0
	v_addc_co_u32_e32 v19, vcc, 0, v143, vcc
	v_add_co_u32_e32 v26, vcc, 0xba11000, v140
	global_load_dwordx4 v[18:21], v[18:19], off offset:256
	s_nop 0
	v_addc_co_u32_e32 v27, vcc, 0, v141, vcc
	v_add_co_u32_e32 v34, vcc, 0x4222000, v142
	global_load_dwordx4 v[26:29], v[26:27], off offset:256
	s_nop 0
	v_addc_co_u32_e32 v35, vcc, 0, v143, vcc
	v_add_co_u32_e32 v42, vcc, 0xba22000, v140
	global_load_dwordx4 v[34:37], v[34:35], off offset:256
	s_nop 0
	v_addc_co_u32_e32 v43, vcc, 0, v141, vcc
	v_add_co_u32_e32 v50, vcc, 0x4233000, v142
	global_load_dwordx4 v[42:45], v[42:43], off offset:256
	s_nop 0
	v_addc_co_u32_e32 v51, vcc, 0, v143, vcc
	v_add_co_u32_e32 v58, vcc, 0xba33000, v140
	global_load_dwordx4 v[50:53], v[50:51], off offset:256
	s_nop 0
	v_addc_co_u32_e32 v59, vcc, 0, v141, vcc
	global_load_dwordx4 v[58:61], v[58:59], off offset:256
; DEV f32x4 mfma16(bf16x8 a, bf16x8 b, f32x4 c) { return __builtin_amdgcn_mfma_f32_16x16x32_bf16(a, b, c, 0, 0, 0); }
; #define G_LOAD(RA, RB, KT) { _Pragma("unroll") for (int i = 0; i < 4; i++) { \
;       RA[i] = *(const u32x4*)(Ap + (size_t)(i * 32) * lda + (KT) * 64); RB[i] = *(const u32x4*)(Bp + (size_t)(i * 32) * ldb + (KT) * 64); } }
; #define G_STORE(RA, RB) { _Pragma("unroll") for (int i = 0; i < 4; i++) { \
;       *(u32x4*)(As + (lrow + i * 32) * GLD + lcc * 8) = RA[i]; *(u32x4*)(Bs + (lrow + i * 32) * GLD + lcc * 8) = RB[i]; } }
; template <int TI, int TJ, int KS>
; DEV void mfma_lds(const bf16_t* Arows, int lda, const bf16_t* Brows, int ldb, int i0, int j0, f32x4 (&acc)[TI][TJ]) {
;     ...
;   for (int ks = 0; ks < KS; ks++) {
;     bf16x8 af[TI], bfr[TJ];
; #pragma unroll
;     for (int i = 0; i < TI; i++) af[i] = *(const bf16x8*)(Arows + (i0 + i * 16 + l15) * lda + ks * 32 + quad * 8);
; #pragma unroll
;     for (int j = 0; j < TJ; j++) bfr[j] = *(const bf16x8*)(Brows + (j0 + j * 16 + l15) * ldb + ks * 32 + quad * 8);
; #pragma unroll
;     for (int i = 0; i < TI; i++)
; #pragma unroll
;       for (int j = 0; j < TJ; j++) acc[i][j] = mfma16(af[i], bfr[j], acc[i][j]);
;   }
; template <class Epi>
; DEV void gemm_tile(const bf16_t* __restrict__ A, int lda, const bf16_t* __restrict__ Bt, int ldb, int K, int m0, int n0,
;                    Epi& epi, char* smem) {
;     ...
;     mfma_lds<4, 4, 2>(Bs, GLD, As, GLD, wn * 64, wm * 64, acc);
;     __syncthreads();
;     G_STORE(ra1, rb1);
;     __syncthreads();
;     if (kt + 3 < nk) G_LOAD(ra1, rb1, kt + 3);
.LBB0_184:
	v_mov_b32_e32 v130, v195
	s_cmp_gt_u32 s12, 12
	v_and_b32_e32 v135, 15, v130
	v_or_b32_e32 v131, v135, v144
	v_and_b32_e32 v148, 48, v130
	v_mul_u32_u24_e32 v130, 0x50, v131
	v_lshl_add_u32 v147, v130, 1, v148
	v_or_b32_e32 v135, v135, v146
	v_mad_u32_u24 v238, v135, s36, v148
	ds_read_b128 v[148:151], v147 offset:20480
	ds_read_b128 v[164:167], v238
	ds_read_b128 v[168:171], v238 offset:2560
	ds_read_b128 v[172:175], v238 offset:5120
	ds_read_b128 v[176:179], v238 offset:7680
	ds_read_b128 v[152:155], v147 offset:23040
	ds_read_b128 v[156:159], v147 offset:25600
	ds_read_b128 v[160:163], v147 offset:28160
	ds_read_b128 v[180:183], v238 offset:64
	ds_read_b128 v[184:187], v238 offset:2624
	s_waitcnt lgkmcnt(8)
	v_mfma_f32_16x16x32_bf16 v[106:109], v[148:151], v[164:167], v[106:109]
	s_waitcnt lgkmcnt(7)
	v_mfma_f32_16x16x32_bf16 v[122:125], v[148:151], v[168:171], v[122:125]
	s_waitcnt lgkmcnt(6)
	v_mfma_f32_16x16x32_bf16 v[114:117], v[148:151], v[172:175], v[114:117]
	s_waitcnt lgkmcnt(5)
	v_mfma_f32_16x16x32_bf16 v[110:113], v[148:151], v[176:179], v[110:113]
	ds_read_b128 v[148:151], v147 offset:20544
	s_waitcnt lgkmcnt(5)
	v_mfma_f32_16x16x32_bf16 v[102:105], v[152:155], v[164:167], v[102:105]
	v_mfma_f32_16x16x32_bf16 v[94:97], v[152:155], v[168:171], v[94:97]
	v_mfma_f32_16x16x32_bf16 v[86:89], v[152:155], v[172:175], v[86:89]
	v_mfma_f32_16x16x32_bf16 v[78:81], v[152:155], v[176:179], v[78:81]
	ds_read_b128 v[152:155], v147 offset:23104
	s_waitcnt lgkmcnt(5)
	v_mfma_f32_16x16x32_bf16 v[82:85], v[156:159], v[164:167], v[82:85]
	v_mfma_f32_16x16x32_bf16 v[74:77], v[156:159], v[168:171], v[74:77]
	v_mfma_f32_16x16x32_bf16 v[70:73], v[156:159], v[172:175], v[70:73]
	v_mfma_f32_16x16x32_bf16 v[66:69], v[156:159], v[176:179], v[66:69]
	ds_read_b128 v[156:159], v147 offset:25664
	s_waitcnt lgkmcnt(5)
	v_mfma_f32_16x16x32_bf16 v[126:129], v[160:163], v[172:175], v[126:129]
	v_mfma_f32_16x16x32_bf16 v[118:121], v[160:163], v[176:179], v[118:121]
	ds_read_b128 v[172:175], v238 offset:5184
	ds_read_b128 v[176:179], v238 offset:7744
	v_mfma_f32_16x16x32_bf16 v[98:101], v[160:163], v[164:167], v[98:101]
	v_mfma_f32_16x16x32_bf16 v[90:93], v[160:163], v[168:171], v[90:93]
	ds_read_b128 v[160:163], v147 offset:28224
	s_waitcnt lgkmcnt(5)
	v_mfma_f32_16x16x32_bf16 v[106:109], v[148:151], v[180:183], v[106:109]
	s_waitcnt lgkmcnt(4)
	v_mfma_f32_16x16x32_bf16 v[102:105], v[152:155], v[180:183], v[102:105]
	s_waitcnt lgkmcnt(3)
	v_mfma_f32_16x16x32_bf16 v[82:85], v[156:159], v[180:183], v[82:85]
	v_mfma_f32_16x16x32_bf16 v[122:125], v[148:151], v[184:187], v[122:125]
	v_mfma_f32_16x16x32_bf16 v[94:97], v[152:155], v[184:187], v[94:97]
	v_mfma_f32_16x16x32_bf16 v[74:77], v[156:159], v[184:187], v[74:77]
	s_waitcnt lgkmcnt(2)
	v_mfma_f32_16x16x32_bf16 v[114:117], v[148:151], v[172:175], v[114:117]
	v_mfma_f32_16x16x32_bf16 v[86:89], v[152:155], v[172:175], v[86:89]
	v_mfma_f32_16x16x32_bf16 v[70:73], v[156:159], v[172:175], v[70:73]
	s_waitcnt lgkmcnt(1)
	v_mfma_f32_16x16x32_bf16 v[110:113], v[148:151], v[176:179], v[110:113]
	v_mfma_f32_16x16x32_bf16 v[78:81], v[152:155], v[176:179], v[78:81]
	v_mfma_f32_16x16x32_bf16 v[66:69], v[156:159], v[176:179], v[66:69]
	s_waitcnt lgkmcnt(0)
	v_mfma_f32_16x16x32_bf16 v[98:101], v[160:163], v[180:183], v[98:101]
	s_barrier
	v_mfma_f32_16x16x32_bf16 v[90:93], v[160:163], v[184:187], v[90:93]
	s_waitcnt vmcnt(15)
	ds_write_b128 v134, v[6:9]
	s_waitcnt vmcnt(14)
	ds_write_b128 v134, v[14:17] offset:20480
	s_waitcnt vmcnt(13)
	ds_write_b128 v134, v[22:25] offset:5120
	s_waitcnt vmcnt(12)
	ds_write_b128 v134, v[30:33] offset:25600
	s_waitcnt vmcnt(11)
	ds_write_b128 v134, v[38:41] offset:10240
	s_waitcnt vmcnt(10)
	ds_write_b128 v134, v[46:49] offset:30720
	s_waitcnt vmcnt(9)
	ds_write_b128 v134, v[54:57] offset:15360
	s_waitcnt vmcnt(8)
	ds_write_b128 v134, v[62:65] offset:35840
	v_mfma_f32_16x16x32_bf16 v[126:129], v[160:163], v[172:175], v[126:129]
	s_waitcnt lgkmcnt(0)
	s_barrier
	v_mfma_f32_16x16x32_bf16 v[118:121], v[160:163], v[176:179], v[118:121]
	s_cbranch_scc1 .LBB0_181
	v_add_co_u32_e32 v6, vcc, 0x4200000, v142
	s_nop 1
	v_addc_co_u32_e32 v7, vcc, 0, v143, vcc
	v_add_co_u32_e32 v14, vcc, 0xba00000, v140
	global_load_dwordx4 v[6:9], v[6:7], off offset:384
	s_nop 0
	v_addc_co_u32_e32 v15, vcc, 0, v141, vcc
	v_add_co_u32_e32 v22, vcc, 0x4211000, v142
	global_load_dwordx4 v[14:17], v[14:15], off offset:384
	s_nop 0
	v_addc_co_u32_e32 v23, vcc, 0, v143, vcc
	v_add_co_u32_e32 v30, vcc, 0xba11000, v140
	global_load_dwordx4 v[22:25], v[22:23], off offset:384
	s_nop 0
	v_addc_co_u32_e32 v31, vcc, 0, v141, vcc
	v_add_co_u32_e32 v38, vcc, 0x4222000, v142
	global_load_dwordx4 v[30:33], v[30:31], off offset:384
	s_nop 0
	v_addc_co_u32_e32 v39, vcc, 0, v143, vcc
	v_add_co_u32_e32 v46, vcc, 0xba22000, v140
	global_load_dwordx4 v[38:41], v[38:39], off offset:384
	s_nop 0
	v_addc_co_u32_e32 v47, vcc, 0, v141, vcc
	v_add_co_u32_e32 v54, vcc, 0x4233000, v142
	global_load_dwordx4 v[46:49], v[46:47], off offset:384
	s_nop 0
	v_addc_co_u32_e32 v55, vcc, 0, v143, vcc
	v_add_co_u32_e32 v62, vcc, 0xba33000, v140
	global_load_dwordx4 v[54:57], v[54:55], off offset:384
	s_nop 0
	v_addc_co_u32_e32 v63, vcc, 0, v141, vcc
	global_load_dwordx4 v[62:65], v[62:63], off offset:384
	s_branch .LBB0_181

; #define G_LOAD(RA, RB, KT) { _Pragma("unroll") for (int i = 0; i < 4; i++) { \
;       RA[i] = *(const u32x4*)(Ap + (size_t)(i * 32) * lda + (KT) * 64); RB[i] = *(const u32x4*)(Bp + (size_t)(i * 32) * ldb + (KT) * 64); } }
; #define G_STORE(RA, RB) { _Pragma("unroll") for (int i = 0; i < 4; i++) { \
;       *(u32x4*)(As + (lrow + i * 32) * GLD + lcc * 8) = RA[i]; *(u32x4*)(Bs + (lrow + i * 32) * GLD + lcc * 8) = RB[i]; } }
; template <class Epi>
; DEV void gemm_tile(const bf16_t* __restrict__ A, int lda, const bf16_t* __restrict__ Bt, int ldb, int K, int m0, int n0,
;                    Epi& epi, char* smem) {
;     ...
;   G_LOAD(ra0, rb0, 0);
;   G_LOAD(ra1, rb1, 1);
;   for (int kt = 0; kt < nk; kt += 2) {
;     __syncthreads();
;     G_STORE(ra0, rb0);
;     __syncthreads();
;     if (kt + 2 < nk) G_LOAD(ra0, rb0, kt + 2);
.LBB0_201:
	s_add_i32 s1, s1, 2
	s_cmp_gt_u32 s1, 13
	s_cselect_b64 s[16:17], -1, 0
	s_and_b64 vcc, exec, s[16:17]
	v_lshl_add_u64 v[138:139], v[134:135], 0, v[0:1]
	v_lshl_add_u64 v[136:137], v[132:133], 0, v[0:1]
	s_waitcnt lgkmcnt(0)
	s_barrier
	s_waitcnt vmcnt(15)
	ds_write_b128 v130, v[42:45]
	s_waitcnt vmcnt(14)
	ds_write_b128 v130, v[50:53] offset:20480
	s_waitcnt vmcnt(13)
	ds_write_b128 v130, v[58:61] offset:5120
	s_waitcnt vmcnt(12)
	ds_write_b128 v130, v[66:69] offset:25600
	s_waitcnt vmcnt(11)
	ds_write_b128 v130, v[78:81] offset:10240
	s_waitcnt vmcnt(10)
	ds_write_b128 v130, v[86:89] offset:30720
	s_waitcnt vmcnt(9)
	ds_write_b128 v130, v[94:97] offset:15360
	s_waitcnt vmcnt(8)
	ds_write_b128 v130, v[102:105] offset:35840
	s_waitcnt lgkmcnt(0)
	s_barrier
	s_cbranch_vccnz .Lgw_skip_1
	v_add_co_u32_e32 v42, vcc, 0x4200000, v138
	s_nop 1
	v_addc_co_u32_e32 v43, vcc, 0, v139, vcc
	v_add_co_u32_e32 v50, vcc, 0xb3a0000, v136
	global_load_dwordx4 v[42:45], v[42:43], off offset:256
	s_nop 0
	v_addc_co_u32_e32 v51, vcc, 0, v137, vcc
	v_add_co_u32_e32 v58, vcc, 0x4211000, v138
	global_load_dwordx4 v[50:53], v[50:51], off offset:256
	s_nop 0
	v_addc_co_u32_e32 v59, vcc, 0, v139, vcc
	v_add_co_u32_e32 v66, vcc, 0xb3b1000, v136
	global_load_dwordx4 v[58:61], v[58:59], off offset:256
	s_nop 0
	v_addc_co_u32_e32 v67, vcc, 0, v137, vcc
	v_add_co_u32_e32 v78, vcc, 0x4222000, v138
	global_load_dwordx4 v[66:69], v[66:67], off offset:256
	s_nop 0
	v_addc_co_u32_e32 v79, vcc, 0, v139, vcc
	v_add_co_u32_e32 v86, vcc, 0xb3c2000, v136
	global_load_dwordx4 v[78:81], v[78:79], off offset:256
	s_nop 0
	v_addc_co_u32_e32 v87, vcc, 0, v137, vcc
	v_add_co_u32_e32 v94, vcc, 0x4233000, v138
	global_load_dwordx4 v[86:89], v[86:87], off offset:256
	s_nop 0
	v_addc_co_u32_e32 v95, vcc, 0, v139, vcc
	v_add_co_u32_e32 v102, vcc, 0xb3d3000, v136
	global_load_dwordx4 v[94:97], v[94:95], off offset:256
	s_nop 0
	v_addc_co_u32_e32 v103, vcc, 0, v137, vcc
	global_load_dwordx4 v[102:105], v[102:103], off offset:256
; DEV f32x4 mfma16(bf16x8 a, bf16x8 b, f32x4 c) { return __builtin_amdgcn_mfma_f32_16x16x32_bf16(a, b, c, 0, 0, 0); }
; #define G_LOAD(RA, RB, KT) { _Pragma("unroll") for (int i = 0; i < 4; i++) { \
;       RA[i] = *(const u32x4*)(Ap + (size_t)(i * 32) * lda + (KT) * 64); RB[i] = *(const u32x4*)(Bp + (size_t)(i * 32) * ldb + (KT) * 64); } }
; #define G_STORE(RA, RB) { _Pragma("unroll") for (int i = 0; i < 4; i++) { \
;       *(u32x4*)(As + (lrow + i * 32) * GLD + lcc * 8) = RA[i]; *(u32x4*)(Bs + (lrow + i * 32) * GLD + lcc * 8) = RB[i]; } }
; template <int TI, int TJ, int KS>
; DEV void mfma_lds(const bf16_t* Arows, int lda, const bf16_t* Brows, int ldb, int i0, int j0, f32x4 (&acc)[TI][TJ]) {
;     ...
;   for (int ks = 0; ks < KS; ks++) {
;     bf16x8 af[TI], bfr[TJ];
; #pragma unroll
;     for (int i = 0; i < TI; i++) af[i] = *(const bf16x8*)(Arows + (i0 + i * 16 + l15) * lda + ks * 32 + quad * 8);
; #pragma unroll
;     for (int j = 0; j < TJ; j++) bfr[j] = *(const bf16x8*)(Brows + (j0 + j * 16 + l15) * ldb + ks * 32 + quad * 8);
; #pragma unroll
;     for (int i = 0; i < TI; i++)
; #pragma unroll
;       for (int j = 0; j < TJ; j++) acc[i][j] = mfma16(af[i], bfr[j], acc[i][j]);
;   }
; template <class Epi>
; DEV void gemm_tile(const bf16_t* __restrict__ A, int lda, const bf16_t* __restrict__ Bt, int ldb, int K, int m0, int n0,
;                    Epi& epi, char* smem) {
;     ...
;     mfma_lds<4, 4, 2>(Bs, GLD, As, GLD, wn * 64, wm * 64, acc);
;     __syncthreads();
;     G_STORE(ra1, rb1);
;     __syncthreads();
;     if (kt + 3 < nk) G_LOAD(ra1, rb1, kt + 3);
.LBB0_203:
	v_mov_b32_e32 v131, v195
	s_cmp_gt_u32 s1, 12
	v_and_b32_e32 v143, 15, v131
	v_or_b32_e32 v144, v143, v140
	v_and_b32_e32 v148, 48, v131
	v_mul_u32_u24_e32 v131, 0x50, v144
	v_lshl_add_u32 v131, v131, 1, v148
	v_or_b32_e32 v143, v143, v142
	v_mad_u32_u24 v238, v143, s36, v148
	ds_read_b128 v[144:147], v131 offset:20480
	ds_read_b128 v[160:163], v238
	ds_read_b128 v[164:167], v238 offset:2560
	ds_read_b128 v[168:171], v238 offset:5120
	ds_read_b128 v[172:175], v238 offset:7680
	ds_read_b128 v[148:151], v131 offset:23040
	ds_read_b128 v[152:155], v131 offset:25600
	ds_read_b128 v[156:159], v131 offset:28160
	ds_read_b128 v[176:179], v238 offset:64
	ds_read_b128 v[180:183], v238 offset:2624
	s_waitcnt lgkmcnt(8)
	v_mfma_f32_16x16x32_bf16 v[126:129], v[144:147], v[160:163], v[126:129]
	s_waitcnt lgkmcnt(7)
	v_mfma_f32_16x16x32_bf16 v[122:125], v[144:147], v[164:167], v[122:125]
	s_waitcnt lgkmcnt(6)
	v_mfma_f32_16x16x32_bf16 v[118:121], v[144:147], v[168:171], v[118:121]
	s_waitcnt lgkmcnt(5)
	v_mfma_f32_16x16x32_bf16 v[114:117], v[144:147], v[172:175], v[114:117]
	ds_read_b128 v[144:147], v131 offset:20544
	s_waitcnt lgkmcnt(5)
	v_mfma_f32_16x16x32_bf16 v[110:113], v[148:151], v[160:163], v[110:113]
	v_mfma_f32_16x16x32_bf16 v[74:77], v[148:151], v[164:167], v[74:77]
	v_mfma_f32_16x16x32_bf16 v[38:41], v[148:151], v[168:171], v[38:41]
	v_mfma_f32_16x16x32_bf16 v[34:37], v[148:151], v[172:175], v[34:37]
	ds_read_b128 v[148:151], v131 offset:23104
	s_waitcnt lgkmcnt(5)
	v_mfma_f32_16x16x32_bf16 v[30:33], v[152:155], v[160:163], v[30:33]
	v_mfma_f32_16x16x32_bf16 v[26:29], v[152:155], v[164:167], v[26:29]
	v_mfma_f32_16x16x32_bf16 v[22:25], v[152:155], v[168:171], v[22:25]
	v_mfma_f32_16x16x32_bf16 v[18:21], v[152:155], v[172:175], v[18:21]
	ds_read_b128 v[152:155], v131 offset:25664
	s_waitcnt lgkmcnt(5)
	v_mfma_f32_16x16x32_bf16 v[6:9], v[156:159], v[168:171], v[6:9]
	v_mfma_f32_16x16x32_bf16 v[2:5], v[156:159], v[172:175], v[2:5]
	ds_read_b128 v[168:171], v238 offset:5184
	ds_read_b128 v[172:175], v238 offset:7744
	v_mfma_f32_16x16x32_bf16 v[14:17], v[156:159], v[160:163], v[14:17]
	v_mfma_f32_16x16x32_bf16 v[10:13], v[156:159], v[164:167], v[10:13]
	ds_read_b128 v[156:159], v131 offset:28224
	s_waitcnt lgkmcnt(5)
	v_mfma_f32_16x16x32_bf16 v[126:129], v[144:147], v[176:179], v[126:129]
	s_waitcnt lgkmcnt(4)
	v_mfma_f32_16x16x32_bf16 v[110:113], v[148:151], v[176:179], v[110:113]
	s_waitcnt lgkmcnt(3)
	v_mfma_f32_16x16x32_bf16 v[30:33], v[152:155], v[176:179], v[30:33]
	v_mfma_f32_16x16x32_bf16 v[122:125], v[144:147], v[180:183], v[122:125]
	v_mfma_f32_16x16x32_bf16 v[74:77], v[148:151], v[180:183], v[74:77]
	v_mfma_f32_16x16x32_bf16 v[26:29], v[152:155], v[180:183], v[26:29]
	s_waitcnt lgkmcnt(2)
	v_mfma_f32_16x16x32_bf16 v[118:121], v[144:147], v[168:171], v[118:121]
	v_mfma_f32_16x16x32_bf16 v[38:41], v[148:151], v[168:171], v[38:41]
	v_mfma_f32_16x16x32_bf16 v[22:25], v[152:155], v[168:171], v[22:25]
	s_waitcnt lgkmcnt(1)
	v_mfma_f32_16x16x32_bf16 v[114:117], v[144:147], v[172:175], v[114:117]
	v_mfma_f32_16x16x32_bf16 v[34:37], v[148:151], v[172:175], v[34:37]
	v_mfma_f32_16x16x32_bf16 v[18:21], v[152:155], v[172:175], v[18:21]
	s_waitcnt lgkmcnt(0)
	v_mfma_f32_16x16x32_bf16 v[14:17], v[156:159], v[176:179], v[14:17]
	s_barrier
	v_mfma_f32_16x16x32_bf16 v[10:13], v[156:159], v[180:183], v[10:13]
	s_waitcnt vmcnt(15)
	ds_write_b128 v130, v[46:49]
	s_waitcnt vmcnt(14)
	ds_write_b128 v130, v[54:57] offset:20480
	s_waitcnt vmcnt(13)
	ds_write_b128 v130, v[62:65] offset:5120
	s_waitcnt vmcnt(12)
	ds_write_b128 v130, v[70:73] offset:25600
	s_waitcnt vmcnt(11)
	ds_write_b128 v130, v[82:85] offset:10240
	s_waitcnt vmcnt(10)
	ds_write_b128 v130, v[90:93] offset:30720
	s_waitcnt vmcnt(9)
	ds_write_b128 v130, v[98:101] offset:15360
	s_waitcnt vmcnt(8)
	ds_write_b128 v130, v[106:109] offset:35840
	v_mfma_f32_16x16x32_bf16 v[6:9], v[156:159], v[168:171], v[6:9]
	s_waitcnt lgkmcnt(0)
	s_barrier
	v_mfma_f32_16x16x32_bf16 v[2:5], v[156:159], v[172:175], v[2:5]
	s_cbranch_scc1 .LBB0_200
	v_add_co_u32_e32 v46, vcc, 0x4200000, v138
	s_nop 1
	v_addc_co_u32_e32 v47, vcc, 0, v139, vcc
	v_add_co_u32_e32 v54, vcc, 0xb3a0000, v136
	global_load_dwordx4 v[46:49], v[46:47], off offset:384
	s_nop 0
	v_addc_co_u32_e32 v55, vcc, 0, v137, vcc
	v_add_co_u32_e32 v62, vcc, 0x4211000, v138
	global_load_dwordx4 v[54:57], v[54:55], off offset:384
	s_nop 0
	v_addc_co_u32_e32 v63, vcc, 0, v139, vcc
	v_add_co_u32_e32 v70, vcc, 0xb3b1000, v136
	global_load_dwordx4 v[62:65], v[62:63], off offset:384
	s_nop 0
	v_addc_co_u32_e32 v71, vcc, 0, v137, vcc
	v_add_co_u32_e32 v82, vcc, 0x4222000, v138
	global_load_dwordx4 v[70:73], v[70:71], off offset:384
	s_nop 0
	v_addc_co_u32_e32 v83, vcc, 0, v139, vcc
	v_add_co_u32_e32 v90, vcc, 0xb3c2000, v136
	global_load_dwordx4 v[82:85], v[82:83], off offset:384
	s_nop 0
	v_addc_co_u32_e32 v91, vcc, 0, v137, vcc
	v_add_co_u32_e32 v98, vcc, 0x4233000, v138
	global_load_dwordx4 v[90:93], v[90:91], off offset:384
	s_nop 0
	v_addc_co_u32_e32 v99, vcc, 0, v139, vcc
	v_add_co_u32_e32 v106, vcc, 0xb3d3000, v136
	global_load_dwordx4 v[98:101], v[98:99], off offset:384
	s_nop 0
	v_addc_co_u32_e32 v107, vcc, 0, v137, vcc
	global_load_dwordx4 v[106:109], v[106:107], off offset:384
	s_branch .LBB0_200

; #define G_LOAD(RA, RB, KT) { _Pragma("unroll") for (int i = 0; i < 4; i++) { \
;       RA[i] = *(const u32x4*)(Ap + (size_t)(i * 32) * lda + (KT) * 64); RB[i] = *(const u32x4*)(Bp + (size_t)(i * 32) * ldb + (KT) * 64); } }
; #define G_STORE(RA, RB) { _Pragma("unroll") for (int i = 0; i < 4; i++) { \
;       *(u32x4*)(As + (lrow + i * 32) * GLD + lcc * 8) = RA[i]; *(u32x4*)(Bs + (lrow + i * 32) * GLD + lcc * 8) = RB[i]; } }
; template <class Epi>
; DEV void gemm_tile(const bf16_t* __restrict__ A, int lda, const bf16_t* __restrict__ Bt, int ldb, int K, int m0, int n0,
;                    Epi& epi, char* smem) {
;     ...
;   G_LOAD(ra0, rb0, 0);
;   G_LOAD(ra1, rb1, 1);
;   for (int kt = 0; kt < nk; kt += 2) {
;     __syncthreads();
;     G_STORE(ra0, rb0);
;     __syncthreads();
;     if (kt + 2 < nk) G_LOAD(ra0, rb0, kt + 2);
.LBB0_325:
	s_add_i32 s1, s1, 2
	s_cmp_gt_u32 s1, 13
	s_cselect_b64 s[6:7], -1, 0
	s_and_b64 vcc, exec, s[6:7]
	v_lshl_add_u64 v[138:139], v[134:135], 0, v[0:1]
	v_lshl_add_u64 v[136:137], v[132:133], 0, v[0:1]
	s_waitcnt lgkmcnt(0)
	s_barrier
	s_waitcnt vmcnt(15)
	ds_write_b128 v130, v[66:69]
	s_waitcnt vmcnt(14)
	ds_write_b128 v130, v[74:77] offset:20480
	s_waitcnt vmcnt(13)
	ds_write_b128 v130, v[82:85] offset:5120
	s_waitcnt vmcnt(12)
	ds_write_b128 v130, v[90:93] offset:25600
	s_waitcnt vmcnt(11)
	ds_write_b128 v130, v[98:101] offset:10240
	s_waitcnt vmcnt(10)
	ds_write_b128 v130, v[106:109] offset:30720
	s_waitcnt vmcnt(9)
	ds_write_b128 v130, v[114:117] offset:15360
	s_waitcnt vmcnt(8)
	ds_write_b128 v130, v[122:125] offset:35840
	s_waitcnt lgkmcnt(0)
	s_barrier
	s_cbranch_vccnz .Lgw_skip_2
	v_add_co_u32_e32 v66, vcc, 0x4200000, v138
	s_nop 1
	v_addc_co_u32_e32 v67, vcc, 0, v139, vcc
	v_add_co_u32_e32 v74, vcc, 0xa900000, v136
	global_load_dwordx4 v[66:69], v[66:67], off offset:256
	s_nop 0
	v_addc_co_u32_e32 v75, vcc, 0, v137, vcc
	v_add_co_u32_e32 v82, vcc, 0x4211000, v138
	global_load_dwordx4 v[74:77], v[74:75], off offset:256
	s_nop 0
	v_addc_co_u32_e32 v83, vcc, 0, v139, vcc
	v_add_co_u32_e32 v90, vcc, 0xa911000, v136
	global_load_dwordx4 v[82:85], v[82:83], off offset:256
	s_nop 0
	v_addc_co_u32_e32 v91, vcc, 0, v137, vcc
	v_add_co_u32_e32 v98, vcc, 0x4222000, v138
	global_load_dwordx4 v[90:93], v[90:91], off offset:256
	s_nop 0
	v_addc_co_u32_e32 v99, vcc, 0, v139, vcc
	v_add_co_u32_e32 v106, vcc, 0xa922000, v136
	global_load_dwordx4 v[98:101], v[98:99], off offset:256
	s_nop 0
	v_addc_co_u32_e32 v107, vcc, 0, v137, vcc
	v_add_co_u32_e32 v114, vcc, 0x4233000, v138
	global_load_dwordx4 v[106:109], v[106:107], off offset:256
	s_nop 0
	v_addc_co_u32_e32 v115, vcc, 0, v139, vcc
	v_add_co_u32_e32 v122, vcc, 0xa933000, v136
	global_load_dwordx4 v[114:117], v[114:115], off offset:256
	s_nop 0
	v_addc_co_u32_e32 v123, vcc, 0, v137, vcc
	global_load_dwordx4 v[122:125], v[122:123], off offset:256
; DEV f32x4 mfma16(bf16x8 a, bf16x8 b, f32x4 c) { return __builtin_amdgcn_mfma_f32_16x16x32_bf16(a, b, c, 0, 0, 0); }
; #define G_LOAD(RA, RB, KT) { _Pragma("unroll") for (int i = 0; i < 4; i++) { \
;       RA[i] = *(const u32x4*)(Ap + (size_t)(i * 32) * lda + (KT) * 64); RB[i] = *(const u32x4*)(Bp + (size_t)(i * 32) * ldb + (KT) * 64); } }
; #define G_STORE(RA, RB) { _Pragma("unroll") for (int i = 0; i < 4; i++) { \
;       *(u32x4*)(As + (lrow + i * 32) * GLD + lcc * 8) = RA[i]; *(u32x4*)(Bs + (lrow + i * 32) * GLD + lcc * 8) = RB[i]; } }
; template <int TI, int TJ, int KS>
; DEV void mfma_lds(const bf16_t* Arows, int lda, const bf16_t* Brows, int ldb, int i0, int j0, f32x4 (&acc)[TI][TJ]) {
;     ...
;   for (int ks = 0; ks < KS; ks++) {
;     bf16x8 af[TI], bfr[TJ];
; #pragma unroll
;     for (int i = 0; i < TI; i++) af[i] = *(const bf16x8*)(Arows + (i0 + i * 16 + l15) * lda + ks * 32 + quad * 8);
; #pragma unroll
;     for (int j = 0; j < TJ; j++) bfr[j] = *(const bf16x8*)(Brows + (j0 + j * 16 + l15) * ldb + ks * 32 + quad * 8);
; #pragma unroll
;     for (int i = 0; i < TI; i++)
; #pragma unroll
;       for (int j = 0; j < TJ; j++) acc[i][j] = mfma16(af[i], bfr[j], acc[i][j]);
;   }
; template <class Epi>
; DEV void gemm_tile(const bf16_t* __restrict__ A, int lda, const bf16_t* __restrict__ Bt, int ldb, int K, int m0, int n0,
;                    Epi& epi, char* smem) {
;     ...
;     mfma_lds<4, 4, 2>(Bs, GLD, As, GLD, wn * 64, wm * 64, acc);
;     __syncthreads();
;     G_STORE(ra1, rb1);
;     __syncthreads();
;     if (kt + 3 < nk) G_LOAD(ra1, rb1, kt + 3);
.LBB0_327:
	v_mov_b32_e32 v131, v195
	s_cmp_gt_u32 s1, 12
	v_and_b32_e32 v143, 15, v131
	v_or_b32_e32 v144, v143, v142
	v_and_b32_e32 v148, 48, v131
	v_mul_u32_u24_e32 v131, 0x50, v144
	v_lshl_add_u32 v131, v131, 1, v148
	v_or_b32_e32 v143, v143, v141
	v_mad_u32_u24 v238, v143, s36, v148
	ds_read_b128 v[144:147], v131 offset:20480
	ds_read_b128 v[160:163], v238
	ds_read_b128 v[164:167], v238 offset:2560
	ds_read_b128 v[168:171], v238 offset:5120
	ds_read_b128 v[172:175], v238 offset:7680
	ds_read_b128 v[148:151], v131 offset:23040
	ds_read_b128 v[152:155], v131 offset:25600
	ds_read_b128 v[156:159], v131 offset:28160
	ds_read_b128 v[176:179], v238 offset:64
	ds_read_b128 v[180:183], v238 offset:2624
	s_waitcnt lgkmcnt(8)
	v_mfma_f32_16x16x32_bf16 v[62:65], v[144:147], v[160:163], v[62:65]
	s_waitcnt lgkmcnt(7)
	v_mfma_f32_16x16x32_bf16 v[58:61], v[144:147], v[164:167], v[58:61]
	s_waitcnt lgkmcnt(6)
	v_mfma_f32_16x16x32_bf16 v[54:57], v[144:147], v[168:171], v[54:57]
	s_waitcnt lgkmcnt(5)
	v_mfma_f32_16x16x32_bf16 v[50:53], v[144:147], v[172:175], v[50:53]
	ds_read_b128 v[144:147], v131 offset:20544
	s_waitcnt lgkmcnt(5)
	v_mfma_f32_16x16x32_bf16 v[46:49], v[148:151], v[160:163], v[46:49]
	v_mfma_f32_16x16x32_bf16 v[42:45], v[148:151], v[164:167], v[42:45]
	v_mfma_f32_16x16x32_bf16 v[38:41], v[148:151], v[168:171], v[38:41]
	v_mfma_f32_16x16x32_bf16 v[34:37], v[148:151], v[172:175], v[34:37]
	ds_read_b128 v[148:151], v131 offset:23104
	s_waitcnt lgkmcnt(5)
	v_mfma_f32_16x16x32_bf16 v[30:33], v[152:155], v[160:163], v[30:33]
	v_mfma_f32_16x16x32_bf16 v[26:29], v[152:155], v[164:167], v[26:29]
	v_mfma_f32_16x16x32_bf16 v[22:25], v[152:155], v[168:171], v[22:25]
	v_mfma_f32_16x16x32_bf16 v[18:21], v[152:155], v[172:175], v[18:21]
	ds_read_b128 v[152:155], v131 offset:25664
	s_waitcnt lgkmcnt(5)
	v_mfma_f32_16x16x32_bf16 v[6:9], v[156:159], v[168:171], v[6:9]
	v_mfma_f32_16x16x32_bf16 v[2:5], v[156:159], v[172:175], v[2:5]
	ds_read_b128 v[168:171], v238 offset:5184
	ds_read_b128 v[172:175], v238 offset:7744
	v_mfma_f32_16x16x32_bf16 v[14:17], v[156:159], v[160:163], v[14:17]
	v_mfma_f32_16x16x32_bf16 v[10:13], v[156:159], v[164:167], v[10:13]
	ds_read_b128 v[156:159], v131 offset:28224
	s_waitcnt lgkmcnt(5)
	v_mfma_f32_16x16x32_bf16 v[62:65], v[144:147], v[176:179], v[62:65]
	s_waitcnt lgkmcnt(4)
	v_mfma_f32_16x16x32_bf16 v[46:49], v[148:151], v[176:179], v[46:49]
	s_waitcnt lgkmcnt(3)
	v_mfma_f32_16x16x32_bf16 v[30:33], v[152:155], v[176:179], v[30:33]
	v_mfma_f32_16x16x32_bf16 v[58:61], v[144:147], v[180:183], v[58:61]
	v_mfma_f32_16x16x32_bf16 v[42:45], v[148:151], v[180:183], v[42:45]
	v_mfma_f32_16x16x32_bf16 v[26:29], v[152:155], v[180:183], v[26:29]
	s_waitcnt lgkmcnt(2)
	v_mfma_f32_16x16x32_bf16 v[54:57], v[144:147], v[168:171], v[54:57]
	v_mfma_f32_16x16x32_bf16 v[38:41], v[148:151], v[168:171], v[38:41]
	v_mfma_f32_16x16x32_bf16 v[22:25], v[152:155], v[168:171], v[22:25]
	s_waitcnt lgkmcnt(1)
	v_mfma_f32_16x16x32_bf16 v[50:53], v[144:147], v[172:175], v[50:53]
	v_mfma_f32_16x16x32_bf16 v[34:37], v[148:151], v[172:175], v[34:37]
	v_mfma_f32_16x16x32_bf16 v[18:21], v[152:155], v[172:175], v[18:21]
	s_waitcnt lgkmcnt(0)
	v_mfma_f32_16x16x32_bf16 v[14:17], v[156:159], v[176:179], v[14:17]
	s_barrier
	v_mfma_f32_16x16x32_bf16 v[10:13], v[156:159], v[180:183], v[10:13]
	s_waitcnt vmcnt(15)
	ds_write_b128 v130, v[70:73]
	s_waitcnt vmcnt(14)
	ds_write_b128 v130, v[78:81] offset:20480
	s_waitcnt vmcnt(13)
	ds_write_b128 v130, v[86:89] offset:5120
	s_waitcnt vmcnt(12)
	ds_write_b128 v130, v[94:97] offset:25600
	s_waitcnt vmcnt(11)
	ds_write_b128 v130, v[102:105] offset:10240
	s_waitcnt vmcnt(10)
	ds_write_b128 v130, v[110:113] offset:30720
	s_waitcnt vmcnt(9)
	ds_write_b128 v130, v[118:121] offset:15360
	s_waitcnt vmcnt(8)
	ds_write_b128 v130, v[126:129] offset:35840
	v_mfma_f32_16x16x32_bf16 v[6:9], v[156:159], v[168:171], v[6:9]
	s_waitcnt lgkmcnt(0)
	s_barrier
	v_mfma_f32_16x16x32_bf16 v[2:5], v[156:159], v[172:175], v[2:5]
	s_cbranch_scc1 .LBB0_324
	v_add_co_u32_e32 v70, vcc, 0x4200000, v138
	s_nop 1
	v_addc_co_u32_e32 v71, vcc, 0, v139, vcc
	v_add_co_u32_e32 v78, vcc, 0xa900000, v136
	global_load_dwordx4 v[70:73], v[70:71], off offset:384
	s_nop 0
	v_addc_co_u32_e32 v79, vcc, 0, v137, vcc
	v_add_co_u32_e32 v86, vcc, 0x4211000, v138
	global_load_dwordx4 v[78:81], v[78:79], off offset:384
	s_nop 0
	v_addc_co_u32_e32 v87, vcc, 0, v139, vcc
	v_add_co_u32_e32 v94, vcc, 0xa911000, v136
	global_load_dwordx4 v[86:89], v[86:87], off offset:384
	s_nop 0
	v_addc_co_u32_e32 v95, vcc, 0, v137, vcc
	v_add_co_u32_e32 v102, vcc, 0x4222000, v138
	global_load_dwordx4 v[94:97], v[94:95], off offset:384
	s_nop 0
	v_addc_co_u32_e32 v103, vcc, 0, v139, vcc
	v_add_co_u32_e32 v110, vcc, 0xa922000, v136
	global_load_dwordx4 v[102:105], v[102:103], off offset:384
	s_nop 0
	v_addc_co_u32_e32 v111, vcc, 0, v137, vcc
	v_add_co_u32_e32 v118, vcc, 0x4233000, v138
	global_load_dwordx4 v[110:113], v[110:111], off offset:384
	s_nop 0
	v_addc_co_u32_e32 v119, vcc, 0, v139, vcc
	v_add_co_u32_e32 v126, vcc, 0xa933000, v136
	global_load_dwordx4 v[118:121], v[118:119], off offset:384
	s_nop 0
	v_addc_co_u32_e32 v127, vcc, 0, v137, vcc
	global_load_dwordx4 v[126:129], v[126:127], off offset:384
	s_branch .LBB0_324

; #define G_LOAD(RA, RB, KT) { _Pragma("unroll") for (int i = 0; i < 4; i++) { \
;       RA[i] = *(const u32x4*)(Ap + (size_t)(i * 32) * lda + (KT) * 64); RB[i] = *(const u32x4*)(Bp + (size_t)(i * 32) * ldb + (KT) * 64); } }
; #define G_STORE(RA, RB) { _Pragma("unroll") for (int i = 0; i < 4; i++) { \
;       *(u32x4*)(As + (lrow + i * 32) * GLD + lcc * 8) = RA[i]; *(u32x4*)(Bs + (lrow + i * 32) * GLD + lcc * 8) = RB[i]; } }
; template <class Epi>
; DEV void gemm_tile(const bf16_t* __restrict__ A, int lda, const bf16_t* __restrict__ Bt, int ldb, int K, int m0, int n0,
;                    Epi& epi, char* smem) {
;     ...
;   G_LOAD(ra0, rb0, 0);
;   G_LOAD(ra1, rb1, 1);
;   for (int kt = 0; kt < nk; kt += 2) {
;     __syncthreads();
;     G_STORE(ra0, rb0);
;     __syncthreads();
;     if (kt + 2 < nk) G_LOAD(ra0, rb0, kt + 2);
.LBB0_647:
	s_add_i32 s14, s14, 2
	s_cmp_gt_u32 s14, 13
	s_cselect_b64 s[8:9], -1, 0
	s_and_b64 vcc, exec, s[8:9]
	v_lshl_add_u64 v[142:143], v[138:139], 0, v[0:1]
	v_lshl_add_u64 v[140:141], v[136:137], 0, v[0:1]
	s_waitcnt lgkmcnt(0)
	s_barrier
	s_waitcnt vmcnt(15)
	ds_write_b128 v134, v[2:5]
	s_waitcnt vmcnt(14)
	ds_write_b128 v134, v[10:13] offset:20480
	s_waitcnt vmcnt(13)
	ds_write_b128 v134, v[18:21] offset:5120
	s_waitcnt vmcnt(12)
	ds_write_b128 v134, v[26:29] offset:25600
	s_waitcnt vmcnt(11)
	ds_write_b128 v134, v[34:37] offset:10240
	s_waitcnt vmcnt(10)
	ds_write_b128 v134, v[42:45] offset:30720
	s_waitcnt vmcnt(9)
	ds_write_b128 v134, v[50:53] offset:15360
	s_waitcnt vmcnt(8)
	ds_write_b128 v134, v[58:61] offset:35840
	s_waitcnt lgkmcnt(0)
	s_barrier
	s_cbranch_vccnz .Lgw_skip_3
	v_add_co_u32_e32 v2, vcc, 0x4200000, v142
	s_nop 1
	v_addc_co_u32_e32 v3, vcc, 0, v143, vcc
	v_add_co_u32_e32 v10, vcc, 0xb5c0000, v140
	global_load_dwordx4 v[2:5], v[2:3], off offset:256
	s_nop 0
	v_addc_co_u32_e32 v11, vcc, 0, v141, vcc
	v_add_co_u32_e32 v18, vcc, 0x4211000, v142
	global_load_dwordx4 v[10:13], v[10:11], off offset:256
	s_nop 0
	v_addc_co_u32_e32 v19, vcc, 0, v143, vcc
	v_add_co_u32_e32 v26, vcc, 0xb5d1000, v140
	global_load_dwordx4 v[18:21], v[18:19], off offset:256
	s_nop 0
	v_addc_co_u32_e32 v27, vcc, 0, v141, vcc
	v_add_co_u32_e32 v34, vcc, 0x4222000, v142
	global_load_dwordx4 v[26:29], v[26:27], off offset:256
	s_nop 0
	v_addc_co_u32_e32 v35, vcc, 0, v143, vcc
	v_add_co_u32_e32 v42, vcc, 0xb5e2000, v140
	global_load_dwordx4 v[34:37], v[34:35], off offset:256
	s_nop 0
	v_addc_co_u32_e32 v43, vcc, 0, v141, vcc
	v_add_co_u32_e32 v50, vcc, 0x4233000, v142
	global_load_dwordx4 v[42:45], v[42:43], off offset:256
	s_nop 0
	v_addc_co_u32_e32 v51, vcc, 0, v143, vcc
	v_add_co_u32_e32 v58, vcc, 0xb5f3000, v140
	global_load_dwordx4 v[50:53], v[50:51], off offset:256
	s_nop 0
	v_addc_co_u32_e32 v59, vcc, 0, v141, vcc
	global_load_dwordx4 v[58:61], v[58:59], off offset:256
; DEV f32x4 mfma16(bf16x8 a, bf16x8 b, f32x4 c) { return __builtin_amdgcn_mfma_f32_16x16x32_bf16(a, b, c, 0, 0, 0); }
; #define G_LOAD(RA, RB, KT) { _Pragma("unroll") for (int i = 0; i < 4; i++) { \
;       RA[i] = *(const u32x4*)(Ap + (size_t)(i * 32) * lda + (KT) * 64); RB[i] = *(const u32x4*)(Bp + (size_t)(i * 32) * ldb + (KT) * 64); } }
; #define G_STORE(RA, RB) { _Pragma("unroll") for (int i = 0; i < 4; i++) { \
;       *(u32x4*)(As + (lrow + i * 32) * GLD + lcc * 8) = RA[i]; *(u32x4*)(Bs + (lrow + i * 32) * GLD + lcc * 8) = RB[i]; } }
; template <int TI, int TJ, int KS>
; DEV void mfma_lds(const bf16_t* Arows, int lda, const bf16_t* Brows, int ldb, int i0, int j0, f32x4 (&acc)[TI][TJ]) {
;     ...
;   for (int ks = 0; ks < KS; ks++) {
;     bf16x8 af[TI], bfr[TJ];
; #pragma unroll
;     for (int i = 0; i < TI; i++) af[i] = *(const bf16x8*)(Arows + (i0 + i * 16 + l15) * lda + ks * 32 + quad * 8);
; #pragma unroll
;     for (int j = 0; j < TJ; j++) bfr[j] = *(const bf16x8*)(Brows + (j0 + j * 16 + l15) * ldb + ks * 32 + quad * 8);
; #pragma unroll
;     for (int i = 0; i < TI; i++)
; #pragma unroll
;       for (int j = 0; j < TJ; j++) acc[i][j] = mfma16(af[i], bfr[j], acc[i][j]);
;   }
; template <class Epi>
; DEV void gemm_tile(const bf16_t* __restrict__ A, int lda, const bf16_t* __restrict__ Bt, int ldb, int K, int m0, int n0,
;                    Epi& epi, char* smem) {
;     ...
;     mfma_lds<4, 4, 2>(Bs, GLD, As, GLD, wn * 64, wm * 64, acc);
;     __syncthreads();
;     G_STORE(ra1, rb1);
;     __syncthreads();
;     if (kt + 3 < nk) G_LOAD(ra1, rb1, kt + 3);
.LBB0_649:
	v_mov_b32_e32 v130, v195
	s_cmp_gt_u32 s14, 12
	v_and_b32_e32 v135, 15, v130
	v_or_b32_e32 v131, v135, v144
	v_and_b32_e32 v148, 48, v130
	v_mul_u32_u24_e32 v130, 0x50, v131
	v_lshl_add_u32 v147, v130, 1, v148
	v_or_b32_e32 v135, v135, v146
	v_mad_u32_u24 v238, v135, s36, v148
	ds_read_b128 v[148:151], v147 offset:20480
	ds_read_b128 v[164:167], v238
	ds_read_b128 v[168:171], v238 offset:2560
	ds_read_b128 v[172:175], v238 offset:5120
	ds_read_b128 v[176:179], v238 offset:7680
	ds_read_b128 v[152:155], v147 offset:23040
	ds_read_b128 v[156:159], v147 offset:25600
	ds_read_b128 v[160:163], v147 offset:28160
	ds_read_b128 v[180:183], v238 offset:64
	ds_read_b128 v[184:187], v238 offset:2624
	s_waitcnt lgkmcnt(8)
	v_mfma_f32_16x16x32_bf16 v[106:109], v[148:151], v[164:167], v[106:109]
	s_waitcnt lgkmcnt(7)
	v_mfma_f32_16x16x32_bf16 v[122:125], v[148:151], v[168:171], v[122:125]
	s_waitcnt lgkmcnt(6)
	v_mfma_f32_16x16x32_bf16 v[114:117], v[148:151], v[172:175], v[114:117]
	s_waitcnt lgkmcnt(5)
	v_mfma_f32_16x16x32_bf16 v[110:113], v[148:151], v[176:179], v[110:113]
	ds_read_b128 v[148:151], v147 offset:20544
	s_waitcnt lgkmcnt(5)
	v_mfma_f32_16x16x32_bf16 v[102:105], v[152:155], v[164:167], v[102:105]
	v_mfma_f32_16x16x32_bf16 v[94:97], v[152:155], v[168:171], v[94:97]
	v_mfma_f32_16x16x32_bf16 v[86:89], v[152:155], v[172:175], v[86:89]
	v_mfma_f32_16x16x32_bf16 v[78:81], v[152:155], v[176:179], v[78:81]
	ds_read_b128 v[152:155], v147 offset:23104
	s_waitcnt lgkmcnt(5)
	v_mfma_f32_16x16x32_bf16 v[82:85], v[156:159], v[164:167], v[82:85]
	v_mfma_f32_16x16x32_bf16 v[74:77], v[156:159], v[168:171], v[74:77]
	v_mfma_f32_16x16x32_bf16 v[70:73], v[156:159], v[172:175], v[70:73]
	v_mfma_f32_16x16x32_bf16 v[66:69], v[156:159], v[176:179], v[66:69]
	ds_read_b128 v[156:159], v147 offset:25664
	s_waitcnt lgkmcnt(5)
	v_mfma_f32_16x16x32_bf16 v[126:129], v[160:163], v[172:175], v[126:129]
	v_mfma_f32_16x16x32_bf16 v[118:121], v[160:163], v[176:179], v[118:121]
	ds_read_b128 v[172:175], v238 offset:5184
	ds_read_b128 v[176:179], v238 offset:7744
	v_mfma_f32_16x16x32_bf16 v[98:101], v[160:163], v[164:167], v[98:101]
	v_mfma_f32_16x16x32_bf16 v[90:93], v[160:163], v[168:171], v[90:93]
	ds_read_b128 v[160:163], v147 offset:28224
	s_waitcnt lgkmcnt(5)
	v_mfma_f32_16x16x32_bf16 v[106:109], v[148:151], v[180:183], v[106:109]
	s_waitcnt lgkmcnt(4)
	v_mfma_f32_16x16x32_bf16 v[102:105], v[152:155], v[180:183], v[102:105]
	s_waitcnt lgkmcnt(3)
	v_mfma_f32_16x16x32_bf16 v[82:85], v[156:159], v[180:183], v[82:85]
	v_mfma_f32_16x16x32_bf16 v[122:125], v[148:151], v[184:187], v[122:125]
	v_mfma_f32_16x16x32_bf16 v[94:97], v[152:155], v[184:187], v[94:97]
	v_mfma_f32_16x16x32_bf16 v[74:77], v[156:159], v[184:187], v[74:77]
	s_waitcnt lgkmcnt(2)
	v_mfma_f32_16x16x32_bf16 v[114:117], v[148:151], v[172:175], v[114:117]
	v_mfma_f32_16x16x32_bf16 v[86:89], v[152:155], v[172:175], v[86:89]
	v_mfma_f32_16x16x32_bf16 v[70:73], v[156:159], v[172:175], v[70:73]
	s_waitcnt lgkmcnt(1)
	v_mfma_f32_16x16x32_bf16 v[110:113], v[148:151], v[176:179], v[110:113]
	v_mfma_f32_16x16x32_bf16 v[78:81], v[152:155], v[176:179], v[78:81]
	v_mfma_f32_16x16x32_bf16 v[66:69], v[156:159], v[176:179], v[66:69]
	s_waitcnt lgkmcnt(0)
	v_mfma_f32_16x16x32_bf16 v[98:101], v[160:163], v[180:183], v[98:101]
	s_barrier
	v_mfma_f32_16x16x32_bf16 v[90:93], v[160:163], v[184:187], v[90:93]
	s_waitcnt vmcnt(15)
	ds_write_b128 v134, v[6:9]
	s_waitcnt vmcnt(14)
	ds_write_b128 v134, v[14:17] offset:20480
	s_waitcnt vmcnt(13)
	ds_write_b128 v134, v[22:25] offset:5120
	s_waitcnt vmcnt(12)
	ds_write_b128 v134, v[30:33] offset:25600
	s_waitcnt vmcnt(11)
	ds_write_b128 v134, v[38:41] offset:10240
	s_waitcnt vmcnt(10)
	ds_write_b128 v134, v[46:49] offset:30720
	s_waitcnt vmcnt(9)
	ds_write_b128 v134, v[54:57] offset:15360
	s_waitcnt vmcnt(8)
	ds_write_b128 v134, v[62:65] offset:35840
	v_mfma_f32_16x16x32_bf16 v[126:129], v[160:163], v[172:175], v[126:129]
	s_waitcnt lgkmcnt(0)
	s_barrier
	v_mfma_f32_16x16x32_bf16 v[118:121], v[160:163], v[176:179], v[118:121]
	s_cbranch_scc1 .LBB0_646
	v_add_co_u32_e32 v6, vcc, 0x4200000, v142
	s_nop 1
	v_addc_co_u32_e32 v7, vcc, 0, v143, vcc
	v_add_co_u32_e32 v14, vcc, 0xb5c0000, v140
	global_load_dwordx4 v[6:9], v[6:7], off offset:384
	s_nop 0
	v_addc_co_u32_e32 v15, vcc, 0, v141, vcc
	v_add_co_u32_e32 v22, vcc, 0x4211000, v142
	global_load_dwordx4 v[14:17], v[14:15], off offset:384
	s_nop 0
	v_addc_co_u32_e32 v23, vcc, 0, v143, vcc
	v_add_co_u32_e32 v30, vcc, 0xb5d1000, v140
	global_load_dwordx4 v[22:25], v[22:23], off offset:384
	s_nop 0
	v_addc_co_u32_e32 v31, vcc, 0, v141, vcc
	v_add_co_u32_e32 v38, vcc, 0x4222000, v142
	global_load_dwordx4 v[30:33], v[30:31], off offset:384
	s_nop 0
	v_addc_co_u32_e32 v39, vcc, 0, v143, vcc
	v_add_co_u32_e32 v46, vcc, 0xb5e2000, v140
	global_load_dwordx4 v[38:41], v[38:39], off offset:384
	s_nop 0
	v_addc_co_u32_e32 v47, vcc, 0, v141, vcc
	v_add_co_u32_e32 v54, vcc, 0x4233000, v142
	global_load_dwordx4 v[46:49], v[46:47], off offset:384
	s_nop 0
	v_addc_co_u32_e32 v55, vcc, 0, v143, vcc
	v_add_co_u32_e32 v62, vcc, 0xb5f3000, v140
	global_load_dwordx4 v[54:57], v[54:55], off offset:384
	s_nop 0
	v_addc_co_u32_e32 v63, vcc, 0, v141, vcc
	global_load_dwordx4 v[62:65], v[62:63], off offset:384
	s_branch .LBB0_646

; #define G_LOAD(RA, RB, KT) { _Pragma("unroll") for (int i = 0; i < 4; i++) { \
;       RA[i] = *(const u32x4*)(Ap + (size_t)(i * 32) * lda + (KT) * 64); RB[i] = *(const u32x4*)(Bp + (size_t)(i * 32) * ldb + (KT) * 64); } }
; #define G_STORE(RA, RB) { _Pragma("unroll") for (int i = 0; i < 4; i++) { \
;       *(u32x4*)(As + (lrow + i * 32) * GLD + lcc * 8) = RA[i]; *(u32x4*)(Bs + (lrow + i * 32) * GLD + lcc * 8) = RB[i]; } }
; template <class Epi>
; DEV void gemm_tile(const bf16_t* __restrict__ A, int lda, const bf16_t* __restrict__ Bt, int ldb, int K, int m0, int n0,
;                    Epi& epi, char* smem) {
;     ...
;   G_LOAD(ra0, rb0, 0);
;   G_LOAD(ra1, rb1, 1);
;   for (int kt = 0; kt < nk; kt += 2) {
;     __syncthreads();
;     G_STORE(ra0, rb0);
;     __syncthreads();
;     if (kt + 2 < nk) G_LOAD(ra0, rb0, kt + 2);
.LBB0_671:
	s_add_i32 s15, s15, 2
	s_cmp_gt_u32 s15, 13
	s_cselect_b64 s[8:9], -1, 0
	s_and_b64 vcc, exec, s[8:9]
	v_lshl_add_u64 v[138:139], v[134:135], 0, v[0:1]
	v_lshl_add_u64 v[136:137], v[132:133], 0, v[0:1]
	s_waitcnt lgkmcnt(0)
	s_barrier
	s_waitcnt vmcnt(15)
	ds_write_b128 v130, v[42:45]
	s_waitcnt vmcnt(14)
	ds_write_b128 v130, v[50:53] offset:20480
	s_waitcnt vmcnt(13)
	ds_write_b128 v130, v[62:65] offset:5120
	s_waitcnt vmcnt(12)
	ds_write_b128 v130, v[70:73] offset:25600
	s_waitcnt vmcnt(11)
	ds_write_b128 v130, v[78:81] offset:10240
	s_waitcnt vmcnt(10)
	ds_write_b128 v130, v[86:89] offset:30720
	s_waitcnt vmcnt(9)
	ds_write_b128 v130, v[94:97] offset:15360
	s_waitcnt vmcnt(8)
	ds_write_b128 v130, v[102:105] offset:35840
	s_waitcnt lgkmcnt(0)
	s_barrier
	s_cbranch_vccnz .Lgw_skip_4
	v_add_co_u32_e32 v42, vcc, 0x19700000, v138
	s_nop 1
	v_addc_co_u32_e32 v43, vcc, 0, v139, vcc
	v_add_co_u32_e32 v50, vcc, 0xa6e0000, v136
	global_load_dwordx4 v[42:45], v[42:43], off offset:256
	s_nop 0
	v_addc_co_u32_e32 v51, vcc, 0, v137, vcc
	v_add_co_u32_e32 v62, vcc, 0x19711000, v138
	global_load_dwordx4 v[50:53], v[50:51], off offset:256
	s_nop 0
	v_addc_co_u32_e32 v63, vcc, 0, v139, vcc
	v_add_co_u32_e32 v70, vcc, 0xa6f1000, v136
	global_load_dwordx4 v[62:65], v[62:63], off offset:256
	s_nop 0
	v_addc_co_u32_e32 v71, vcc, 0, v137, vcc
	v_add_co_u32_e32 v78, vcc, 0x19722000, v138
	global_load_dwordx4 v[70:73], v[70:71], off offset:256
	s_nop 0
	v_addc_co_u32_e32 v79, vcc, 0, v139, vcc
	v_add_co_u32_e32 v86, vcc, 0xa702000, v136
	global_load_dwordx4 v[78:81], v[78:79], off offset:256
	s_nop 0
	v_addc_co_u32_e32 v87, vcc, 0, v137, vcc
	v_add_co_u32_e32 v94, vcc, 0x19733000, v138
	global_load_dwordx4 v[86:89], v[86:87], off offset:256
	s_nop 0
	v_addc_co_u32_e32 v95, vcc, 0, v139, vcc
	v_add_co_u32_e32 v102, vcc, 0xa713000, v136
	global_load_dwordx4 v[94:97], v[94:95], off offset:256
	s_nop 0
	v_addc_co_u32_e32 v103, vcc, 0, v137, vcc
	global_load_dwordx4 v[102:105], v[102:103], off offset:256
; DEV f32x4 mfma16(bf16x8 a, bf16x8 b, f32x4 c) { return __builtin_amdgcn_mfma_f32_16x16x32_bf16(a, b, c, 0, 0, 0); }
; #define G_LOAD(RA, RB, KT) { _Pragma("unroll") for (int i = 0; i < 4; i++) { \
;       RA[i] = *(const u32x4*)(Ap + (size_t)(i * 32) * lda + (KT) * 64); RB[i] = *(const u32x4*)(Bp + (size_t)(i * 32) * ldb + (KT) * 64); } }
; #define G_STORE(RA, RB) { _Pragma("unroll") for (int i = 0; i < 4; i++) { \
;       *(u32x4*)(As + (lrow + i * 32) * GLD + lcc * 8) = RA[i]; *(u32x4*)(Bs + (lrow + i * 32) * GLD + lcc * 8) = RB[i]; } }
; template <int TI, int TJ, int KS>
; DEV void mfma_lds(const bf16_t* Arows, int lda, const bf16_t* Brows, int ldb, int i0, int j0, f32x4 (&acc)[TI][TJ]) {
;     ...
;   for (int ks = 0; ks < KS; ks++) {
;     bf16x8 af[TI], bfr[TJ];
; #pragma unroll
;     for (int i = 0; i < TI; i++) af[i] = *(const bf16x8*)(Arows + (i0 + i * 16 + l15) * lda + ks * 32 + quad * 8);
; #pragma unroll
;     for (int j = 0; j < TJ; j++) bfr[j] = *(const bf16x8*)(Brows + (j0 + j * 16 + l15) * ldb + ks * 32 + quad * 8);
; #pragma unroll
;     for (int i = 0; i < TI; i++)
; #pragma unroll
;       for (int j = 0; j < TJ; j++) acc[i][j] = mfma16(af[i], bfr[j], acc[i][j]);
;   }
; template <class Epi>
; DEV void gemm_tile(const bf16_t* __restrict__ A, int lda, const bf16_t* __restrict__ Bt, int ldb, int K, int m0, int n0,
;                    Epi& epi, char* smem) {
;     ...
;     mfma_lds<4, 4, 2>(Bs, GLD, As, GLD, wn * 64, wm * 64, acc);
;     __syncthreads();
;     G_STORE(ra1, rb1);
;     __syncthreads();
;     if (kt + 3 < nk) G_LOAD(ra1, rb1, kt + 3);
.LBB0_673:
	v_mov_b32_e32 v131, v195
	s_cmp_gt_u32 s15, 12
	v_and_b32_e32 v143, 15, v131
	v_or_b32_e32 v144, v143, v140
	v_and_b32_e32 v148, 48, v131
	v_mul_u32_u24_e32 v131, 0x50, v144
	v_lshl_add_u32 v131, v131, 1, v148
	v_or_b32_e32 v143, v143, v142
	v_mad_u32_u24 v238, v143, s36, v148
	ds_read_b128 v[144:147], v131 offset:20480
	ds_read_b128 v[160:163], v238
	ds_read_b128 v[164:167], v238 offset:2560
	ds_read_b128 v[168:171], v238 offset:5120
	ds_read_b128 v[172:175], v238 offset:7680
	ds_read_b128 v[148:151], v131 offset:23040
	ds_read_b128 v[152:155], v131 offset:25600
	ds_read_b128 v[156:159], v131 offset:28160
	ds_read_b128 v[176:179], v238 offset:64
	ds_read_b128 v[180:183], v238 offset:2624
	s_waitcnt lgkmcnt(8)
	v_mfma_f32_16x16x32_bf16 v[126:129], v[144:147], v[160:163], v[126:129]
	s_waitcnt lgkmcnt(7)
	v_mfma_f32_16x16x32_bf16 v[122:125], v[144:147], v[164:167], v[122:125]
	s_waitcnt lgkmcnt(6)
	v_mfma_f32_16x16x32_bf16 v[118:121], v[144:147], v[168:171], v[118:121]
	s_waitcnt lgkmcnt(5)
	v_mfma_f32_16x16x32_bf16 v[114:117], v[144:147], v[172:175], v[114:117]
	ds_read_b128 v[144:147], v131 offset:20544
	s_waitcnt lgkmcnt(5)
	v_mfma_f32_16x16x32_bf16 v[110:113], v[148:151], v[160:163], v[110:113]
	v_mfma_f32_16x16x32_bf16 v[58:61], v[148:151], v[164:167], v[58:61]
	v_mfma_f32_16x16x32_bf16 v[38:41], v[148:151], v[168:171], v[38:41]
	v_mfma_f32_16x16x32_bf16 v[34:37], v[148:151], v[172:175], v[34:37]
	ds_read_b128 v[148:151], v131 offset:23104
	s_waitcnt lgkmcnt(5)
	v_mfma_f32_16x16x32_bf16 v[30:33], v[152:155], v[160:163], v[30:33]
	v_mfma_f32_16x16x32_bf16 v[26:29], v[152:155], v[164:167], v[26:29]
	v_mfma_f32_16x16x32_bf16 v[22:25], v[152:155], v[168:171], v[22:25]
	v_mfma_f32_16x16x32_bf16 v[18:21], v[152:155], v[172:175], v[18:21]
	ds_read_b128 v[152:155], v131 offset:25664
	s_waitcnt lgkmcnt(5)
	v_mfma_f32_16x16x32_bf16 v[6:9], v[156:159], v[168:171], v[6:9]
	v_mfma_f32_16x16x32_bf16 v[2:5], v[156:159], v[172:175], v[2:5]
	ds_read_b128 v[168:171], v238 offset:5184
	ds_read_b128 v[172:175], v238 offset:7744
	v_mfma_f32_16x16x32_bf16 v[14:17], v[156:159], v[160:163], v[14:17]
	v_mfma_f32_16x16x32_bf16 v[10:13], v[156:159], v[164:167], v[10:13]
	ds_read_b128 v[156:159], v131 offset:28224
	s_waitcnt lgkmcnt(5)
	v_mfma_f32_16x16x32_bf16 v[126:129], v[144:147], v[176:179], v[126:129]
	s_waitcnt lgkmcnt(4)
	v_mfma_f32_16x16x32_bf16 v[110:113], v[148:151], v[176:179], v[110:113]
	s_waitcnt lgkmcnt(3)
	v_mfma_f32_16x16x32_bf16 v[30:33], v[152:155], v[176:179], v[30:33]
	v_mfma_f32_16x16x32_bf16 v[122:125], v[144:147], v[180:183], v[122:125]
	v_mfma_f32_16x16x32_bf16 v[58:61], v[148:151], v[180:183], v[58:61]
	v_mfma_f32_16x16x32_bf16 v[26:29], v[152:155], v[180:183], v[26:29]
	s_waitcnt lgkmcnt(2)
	v_mfma_f32_16x16x32_bf16 v[118:121], v[144:147], v[168:171], v[118:121]
	v_mfma_f32_16x16x32_bf16 v[38:41], v[148:151], v[168:171], v[38:41]
	v_mfma_f32_16x16x32_bf16 v[22:25], v[152:155], v[168:171], v[22:25]
	s_waitcnt lgkmcnt(1)
	v_mfma_f32_16x16x32_bf16 v[114:117], v[144:147], v[172:175], v[114:117]
	v_mfma_f32_16x16x32_bf16 v[34:37], v[148:151], v[172:175], v[34:37]
	v_mfma_f32_16x16x32_bf16 v[18:21], v[152:155], v[172:175], v[18:21]
	s_waitcnt lgkmcnt(0)
	v_mfma_f32_16x16x32_bf16 v[14:17], v[156:159], v[176:179], v[14:17]
	s_barrier
	v_mfma_f32_16x16x32_bf16 v[10:13], v[156:159], v[180:183], v[10:13]
	s_waitcnt vmcnt(15)
	ds_write_b128 v130, v[46:49]
	s_waitcnt vmcnt(14)
	ds_write_b128 v130, v[54:57] offset:20480
	s_waitcnt vmcnt(13)
	ds_write_b128 v130, v[66:69] offset:5120
	s_waitcnt vmcnt(12)
	ds_write_b128 v130, v[74:77] offset:25600
	s_waitcnt vmcnt(11)
	ds_write_b128 v130, v[82:85] offset:10240
	s_waitcnt vmcnt(10)
	ds_write_b128 v130, v[90:93] offset:30720
	s_waitcnt vmcnt(9)
	ds_write_b128 v130, v[98:101] offset:15360
	s_waitcnt vmcnt(8)
	ds_write_b128 v130, v[106:109] offset:35840
	v_mfma_f32_16x16x32_bf16 v[6:9], v[156:159], v[168:171], v[6:9]
	s_waitcnt lgkmcnt(0)
	s_barrier
	v_mfma_f32_16x16x32_bf16 v[2:5], v[156:159], v[172:175], v[2:5]
	s_cbranch_scc1 .LBB0_670
	v_add_co_u32_e32 v46, vcc, 0x19700000, v138
	s_nop 1
	v_addc_co_u32_e32 v47, vcc, 0, v139, vcc
	v_add_co_u32_e32 v54, vcc, 0xa6e0000, v136
	global_load_dwordx4 v[46:49], v[46:47], off offset:384
	s_nop 0
	v_addc_co_u32_e32 v55, vcc, 0, v137, vcc
	v_add_co_u32_e32 v66, vcc, 0x19711000, v138
	global_load_dwordx4 v[54:57], v[54:55], off offset:384
	s_nop 0
	v_addc_co_u32_e32 v67, vcc, 0, v139, vcc
	v_add_co_u32_e32 v74, vcc, 0xa6f1000, v136
	global_load_dwordx4 v[66:69], v[66:67], off offset:384
	s_nop 0
	v_addc_co_u32_e32 v75, vcc, 0, v137, vcc
	v_add_co_u32_e32 v82, vcc, 0x19722000, v138
	global_load_dwordx4 v[74:77], v[74:75], off offset:384
	s_nop 0
	v_addc_co_u32_e32 v83, vcc, 0, v139, vcc
	v_add_co_u32_e32 v90, vcc, 0xa702000, v136
	global_load_dwordx4 v[82:85], v[82:83], off offset:384
	s_nop 0
	v_addc_co_u32_e32 v91, vcc, 0, v137, vcc
	v_add_co_u32_e32 v98, vcc, 0x19733000, v138
	global_load_dwordx4 v[90:93], v[90:91], off offset:384
	s_nop 0
	v_addc_co_u32_e32 v99, vcc, 0, v139, vcc
	v_add_co_u32_e32 v106, vcc, 0xa713000, v136
	global_load_dwordx4 v[98:101], v[98:99], off offset:384
	s_nop 0
	v_addc_co_u32_e32 v107, vcc, 0, v137, vcc
	global_load_dwordx4 v[106:109], v[106:107], off offset:384
	s_branch .LBB0_670

; #define G_LOAD(RA, RB, KT) { _Pragma("unroll") for (int i = 0; i < 4; i++) { \
;       RA[i] = *(const u32x4*)(Ap + (size_t)(i * 32) * lda + (KT) * 64); RB[i] = *(const u32x4*)(Bp + (size_t)(i * 32) * ldb + (KT) * 64); } }
; #define G_STORE(RA, RB) { _Pragma("unroll") for (int i = 0; i < 4; i++) { \
;       *(u32x4*)(As + (lrow + i * 32) * GLD + lcc * 8) = RA[i]; *(u32x4*)(Bs + (lrow + i * 32) * GLD + lcc * 8) = RB[i]; } }
; template <class Epi>
; DEV void gemm_tile(const bf16_t* __restrict__ A, int lda, const bf16_t* __restrict__ Bt, int ldb, int K, int m0, int n0,
;                    Epi& epi, char* smem) {
;     ...
;   G_LOAD(ra0, rb0, 0);
;   G_LOAD(ra1, rb1, 1);
;   for (int kt = 0; kt < nk; kt += 2) {
;     __syncthreads();
;     G_STORE(ra0, rb0);
;     __syncthreads();
;     if (kt + 2 < nk) G_LOAD(ra0, rb0, kt + 2);
.LBB0_1039:
	s_add_i32 s14, s14, 2
	s_cmp_gt_u32 s14, 13
	s_cselect_b64 s[8:9], -1, 0
	s_and_b64 vcc, exec, s[8:9]
	v_lshl_add_u64 v[138:139], v[134:135], 0, v[0:1]
	v_lshl_add_u64 v[136:137], v[132:133], 0, v[0:1]
	s_waitcnt lgkmcnt(0)
	s_barrier
	s_waitcnt vmcnt(15)
	ds_write_b128 v130, v[2:5]
	s_waitcnt vmcnt(14)
	ds_write_b128 v130, v[10:13] offset:20480
	s_waitcnt vmcnt(13)
	ds_write_b128 v130, v[18:21] offset:5120
	s_waitcnt vmcnt(12)
	ds_write_b128 v130, v[26:29] offset:25600
	s_waitcnt vmcnt(11)
	ds_write_b128 v130, v[34:37] offset:10240
	s_waitcnt vmcnt(10)
	ds_write_b128 v130, v[42:45] offset:30720
	s_waitcnt vmcnt(9)
	ds_write_b128 v130, v[50:53] offset:15360
	s_waitcnt vmcnt(8)
	ds_write_b128 v130, v[58:61] offset:35840
	s_waitcnt lgkmcnt(0)
	s_barrier
	s_cbranch_vccnz .Lgw_skip_5
	v_add_co_u32_e32 v2, vcc, 0x4200000, v138
	s_nop 1
	v_addc_co_u32_e32 v3, vcc, 0, v139, vcc
	v_add_co_u32_e32 v10, vcc, 0xa300000, v136
	global_load_dwordx4 v[2:5], v[2:3], off offset:256
	s_nop 0
	v_addc_co_u32_e32 v11, vcc, 0, v137, vcc
	v_add_co_u32_e32 v18, vcc, 0x4211000, v138
	global_load_dwordx4 v[10:13], v[10:11], off offset:256
	s_nop 0
	v_addc_co_u32_e32 v19, vcc, 0, v139, vcc
	v_add_co_u32_e32 v26, vcc, 0xa311000, v136
	global_load_dwordx4 v[18:21], v[18:19], off offset:256
	s_nop 0
	v_addc_co_u32_e32 v27, vcc, 0, v137, vcc
	v_add_co_u32_e32 v34, vcc, 0x4222000, v138
	global_load_dwordx4 v[26:29], v[26:27], off offset:256
	s_nop 0
	v_addc_co_u32_e32 v35, vcc, 0, v139, vcc
	v_add_co_u32_e32 v42, vcc, 0xa322000, v136
	global_load_dwordx4 v[34:37], v[34:35], off offset:256
	s_nop 0
	v_addc_co_u32_e32 v43, vcc, 0, v137, vcc
	v_add_co_u32_e32 v50, vcc, 0x4233000, v138
	global_load_dwordx4 v[42:45], v[42:43], off offset:256
	s_nop 0
	v_addc_co_u32_e32 v51, vcc, 0, v139, vcc
	v_add_co_u32_e32 v58, vcc, 0xa333000, v136
	global_load_dwordx4 v[50:53], v[50:51], off offset:256
	s_nop 0
	v_addc_co_u32_e32 v59, vcc, 0, v137, vcc
	global_load_dwordx4 v[58:61], v[58:59], off offset:256
; DEV f32x4 mfma16(bf16x8 a, bf16x8 b, f32x4 c) { return __builtin_amdgcn_mfma_f32_16x16x32_bf16(a, b, c, 0, 0, 0); }
; #define G_LOAD(RA, RB, KT) { _Pragma("unroll") for (int i = 0; i < 4; i++) { \
;       RA[i] = *(const u32x4*)(Ap + (size_t)(i * 32) * lda + (KT) * 64); RB[i] = *(const u32x4*)(Bp + (size_t)(i * 32) * ldb + (KT) * 64); } }
; #define G_STORE(RA, RB) { _Pragma("unroll") for (int i = 0; i < 4; i++) { \
;       *(u32x4*)(As + (lrow + i * 32) * GLD + lcc * 8) = RA[i]; *(u32x4*)(Bs + (lrow + i * 32) * GLD + lcc * 8) = RB[i]; } }
; template <int TI, int TJ, int KS>
; DEV void mfma_lds(const bf16_t* Arows, int lda, const bf16_t* Brows, int ldb, int i0, int j0, f32x4 (&acc)[TI][TJ]) {
;     ...
;   for (int ks = 0; ks < KS; ks++) {
;     bf16x8 af[TI], bfr[TJ];
; #pragma unroll
;     for (int i = 0; i < TI; i++) af[i] = *(const bf16x8*)(Arows + (i0 + i * 16 + l15) * lda + ks * 32 + quad * 8);
; #pragma unroll
;     for (int j = 0; j < TJ; j++) bfr[j] = *(const bf16x8*)(Brows + (j0 + j * 16 + l15) * ldb + ks * 32 + quad * 8);
; #pragma unroll
;     for (int i = 0; i < TI; i++)
; #pragma unroll
;       for (int j = 0; j < TJ; j++) acc[i][j] = mfma16(af[i], bfr[j], acc[i][j]);
;   }
; template <class Epi>
; DEV void gemm_tile(const bf16_t* __restrict__ A, int lda, const bf16_t* __restrict__ Bt, int ldb, int K, int m0, int n0,
;                    Epi& epi, char* smem) {
;     ...
;     mfma_lds<4, 4, 2>(Bs, GLD, As, GLD, wn * 64, wm * 64, acc);
;     __syncthreads();
;     G_STORE(ra1, rb1);
;     __syncthreads();
;     if (kt + 3 < nk) G_LOAD(ra1, rb1, kt + 3);
.LBB0_1041:
	v_mov_b32_e32 v131, v195
	s_cmp_gt_u32 s14, 12
	v_and_b32_e32 v143, 15, v131
	v_or_b32_e32 v144, v143, v141
	v_and_b32_e32 v148, 48, v131
	v_mul_u32_u24_e32 v131, 0x50, v144
	v_lshl_add_u32 v131, v131, 1, v148
	v_or_b32_e32 v143, v143, v142
	v_mad_u32_u24 v238, v143, s36, v148
	ds_read_b128 v[148:151], v131 offset:20480
	ds_read_b128 v[164:167], v238
	ds_read_b128 v[168:171], v238 offset:2560
	ds_read_b128 v[172:175], v238 offset:5120
	ds_read_b128 v[176:179], v238 offset:7680
	ds_read_b128 v[152:155], v131 offset:23040
	ds_read_b128 v[156:159], v131 offset:25600
	ds_read_b128 v[160:163], v131 offset:28160
	ds_read_b128 v[180:183], v238 offset:64
	ds_read_b128 v[184:187], v238 offset:2624
	s_waitcnt lgkmcnt(8)
	v_mfma_f32_16x16x32_bf16 v[114:117], v[148:151], v[164:167], v[114:117]
	s_waitcnt lgkmcnt(7)
	v_mfma_f32_16x16x32_bf16 v[126:129], v[148:151], v[168:171], v[126:129]
	s_waitcnt lgkmcnt(6)
	v_mfma_f32_16x16x32_bf16 v[122:125], v[148:151], v[172:175], v[122:125]
	s_waitcnt lgkmcnt(5)
	v_mfma_f32_16x16x32_bf16 v[118:121], v[148:151], v[176:179], v[118:121]
	ds_read_b128 v[148:151], v131 offset:20544
	s_waitcnt lgkmcnt(5)
	v_mfma_f32_16x16x32_bf16 v[110:113], v[152:155], v[164:167], v[110:113]
	v_mfma_f32_16x16x32_bf16 v[106:109], v[152:155], v[168:171], v[106:109]
	v_mfma_f32_16x16x32_bf16 v[102:105], v[152:155], v[172:175], v[102:105]
	v_mfma_f32_16x16x32_bf16 v[98:101], v[152:155], v[176:179], v[98:101]
	ds_read_b128 v[152:155], v131 offset:23104
	s_waitcnt lgkmcnt(5)
	v_mfma_f32_16x16x32_bf16 v[94:97], v[156:159], v[164:167], v[94:97]
	v_mfma_f32_16x16x32_bf16 v[82:85], v[156:159], v[168:171], v[82:85]
	v_mfma_f32_16x16x32_bf16 v[78:81], v[156:159], v[172:175], v[78:81]
	v_mfma_f32_16x16x32_bf16 v[70:73], v[156:159], v[176:179], v[70:73]
	ds_read_b128 v[156:159], v131 offset:25664
	s_waitcnt lgkmcnt(5)
	v_mfma_f32_16x16x32_bf16 v[66:69], v[160:163], v[172:175], v[66:69]
	v_mfma_f32_16x16x32_bf16 v[90:93], v[160:163], v[176:179], v[90:93]
	ds_read_b128 v[172:175], v238 offset:5184
	ds_read_b128 v[176:179], v238 offset:7744
	v_mfma_f32_16x16x32_bf16 v[86:89], v[160:163], v[164:167], v[86:89]
	v_mfma_f32_16x16x32_bf16 v[74:77], v[160:163], v[168:171], v[74:77]
	ds_read_b128 v[160:163], v131 offset:28224
	s_waitcnt lgkmcnt(5)
	v_mfma_f32_16x16x32_bf16 v[114:117], v[148:151], v[180:183], v[114:117]
	s_waitcnt lgkmcnt(4)
	v_mfma_f32_16x16x32_bf16 v[110:113], v[152:155], v[180:183], v[110:113]
	s_waitcnt lgkmcnt(3)
	v_mfma_f32_16x16x32_bf16 v[94:97], v[156:159], v[180:183], v[94:97]
	v_mfma_f32_16x16x32_bf16 v[126:129], v[148:151], v[184:187], v[126:129]
	v_mfma_f32_16x16x32_bf16 v[106:109], v[152:155], v[184:187], v[106:109]
	v_mfma_f32_16x16x32_bf16 v[82:85], v[156:159], v[184:187], v[82:85]
	s_waitcnt lgkmcnt(2)
	v_mfma_f32_16x16x32_bf16 v[122:125], v[148:151], v[172:175], v[122:125]
	v_mfma_f32_16x16x32_bf16 v[102:105], v[152:155], v[172:175], v[102:105]
	v_mfma_f32_16x16x32_bf16 v[78:81], v[156:159], v[172:175], v[78:81]
	s_waitcnt lgkmcnt(1)
	v_mfma_f32_16x16x32_bf16 v[118:121], v[148:151], v[176:179], v[118:121]
	v_mfma_f32_16x16x32_bf16 v[98:101], v[152:155], v[176:179], v[98:101]
	v_mfma_f32_16x16x32_bf16 v[70:73], v[156:159], v[176:179], v[70:73]
	s_waitcnt lgkmcnt(0)
	v_mfma_f32_16x16x32_bf16 v[86:89], v[160:163], v[180:183], v[86:89]
	s_barrier
	v_mfma_f32_16x16x32_bf16 v[74:77], v[160:163], v[184:187], v[74:77]
	s_waitcnt vmcnt(15)
	ds_write_b128 v130, v[6:9]
	s_waitcnt vmcnt(14)
	ds_write_b128 v130, v[14:17] offset:20480
	s_waitcnt vmcnt(13)
	ds_write_b128 v130, v[22:25] offset:5120
	s_waitcnt vmcnt(12)
	ds_write_b128 v130, v[30:33] offset:25600
	s_waitcnt vmcnt(11)
	ds_write_b128 v130, v[38:41] offset:10240
	s_waitcnt vmcnt(10)
	ds_write_b128 v130, v[46:49] offset:30720
	s_waitcnt vmcnt(9)
	ds_write_b128 v130, v[54:57] offset:15360
	s_waitcnt vmcnt(8)
	ds_write_b128 v130, v[62:65] offset:35840
	v_mfma_f32_16x16x32_bf16 v[66:69], v[160:163], v[172:175], v[66:69]
	s_waitcnt lgkmcnt(0)
	s_barrier
	v_mfma_f32_16x16x32_bf16 v[90:93], v[160:163], v[176:179], v[90:93]
	s_cbranch_scc1 .LBB0_1038
	v_add_co_u32_e32 v6, vcc, 0x4200000, v138
	s_nop 1
	v_addc_co_u32_e32 v7, vcc, 0, v139, vcc
	v_add_co_u32_e32 v14, vcc, 0xa300000, v136
	global_load_dwordx4 v[6:9], v[6:7], off offset:384
	s_nop 0
	v_addc_co_u32_e32 v15, vcc, 0, v137, vcc
	v_add_co_u32_e32 v22, vcc, 0x4211000, v138
	global_load_dwordx4 v[14:17], v[14:15], off offset:384
	s_nop 0
	v_addc_co_u32_e32 v23, vcc, 0, v139, vcc
	v_add_co_u32_e32 v30, vcc, 0xa311000, v136
	global_load_dwordx4 v[22:25], v[22:23], off offset:384
	s_nop 0
	v_addc_co_u32_e32 v31, vcc, 0, v137, vcc
	v_add_co_u32_e32 v38, vcc, 0x4222000, v138
	global_load_dwordx4 v[30:33], v[30:31], off offset:384
	s_nop 0
	v_addc_co_u32_e32 v39, vcc, 0, v139, vcc
	v_add_co_u32_e32 v46, vcc, 0xa322000, v136
	global_load_dwordx4 v[38:41], v[38:39], off offset:384
	s_nop 0
	v_addc_co_u32_e32 v47, vcc, 0, v137, vcc
	v_add_co_u32_e32 v54, vcc, 0x4233000, v138
	global_load_dwordx4 v[46:49], v[46:47], off offset:384
	s_nop 0
	v_addc_co_u32_e32 v55, vcc, 0, v139, vcc
	v_add_co_u32_e32 v62, vcc, 0xa333000, v136
	global_load_dwordx4 v[54:57], v[54:55], off offset:384
	s_nop 0
	v_addc_co_u32_e32 v63, vcc, 0, v137, vcc
	global_load_dwordx4 v[62:65], v[62:63], off offset:384
	s_branch .LBB0_1038
